# mixer short conv: each load of a 4-token iteration is followed by a cache-warming load of the same row 4 tokens ahead (next iteration) into a dead register quad; vmcnt waits re-derived for the interle
# baseline (speedup 1.0000x reference)
.Lmx_conv:
	v_mov_b32_e32 v252, 0x6000
	v_mov_b32_e32 v253, 0
	s_cmp_lt_i32 s25, 1
	s_cbranch_scc1 .LBB0_114
	s_add_i32 s39, s24, s25
	s_add_u32 s30, s8, 0x13100400
	s_addc_u32 s31, s9, 0
	s_add_i32 s4, s24, 1
	v_and_b32_e32 v36, 64, v213
	s_ashr_i32 s5, s4, 31
	v_xor_b32_e32 v0, 1, v213
	v_add_u32_e32 v36, 64, v36
	s_lshl_b64 s[6:7], s[4:5], 11
	v_cmp_lt_i32_e32 vcc, v0, v36
	s_add_u32 s26, s30, s6
	s_addc_u32 s27, s31, s7
	v_cndmask_b32_e32 v0, v213, v0, vcc
	s_add_i32 s5, s34, 0x1800
	v_lshlrev_b32_e32 v106, 2, v0
	v_xor_b32_e32 v0, 2, v213
	s_mul_hi_i32 s4, s4, 0x1800
	s_add_u32 s28, s8, s5
	v_cmp_lt_i32_e32 vcc, v0, v36
	s_addc_u32 s29, s9, s4
	s_ashr_i32 s25, s24, 31
	v_cndmask_b32_e32 v0, v213, v0, vcc
	s_lshl_b64 s[4:5], s[24:25], 11
	v_lshlrev_b32_e32 v107, 2, v0
	v_xor_b32_e32 v0, 4, v213
	s_add_u32 s30, s30, s4
	v_cmp_lt_i32_e32 vcc, v0, v36
	s_addc_u32 s31, s31, s5
	v_mov_b32_e32 v35, v1
	v_cndmask_b32_e32 v0, v213, v0, vcc
	s_mul_hi_i32 s4, s24, 0x1800
	s_add_u32 s34, s8, s34
	v_lshl_add_u64 v[82:83], s[20:21], 0, v[34:35]
	v_lshlrev_b32_e32 v108, 2, v0
	v_lshl_add_u64 v[84:85], s[22:23], 0, v[34:35]
	v_lshlrev_b32_e32 v0, 4, v112
	s_addc_u32 s35, s9, s4
.LBB0_113:
	s_nop 0
	v_lshl_add_u64 v[34:35], s[34:35], 0, v[0:1]
	v_add_co_u32_e32 v36, vcc, 0x7100000, v34
	s_mov_b32 s4, 0x7100000
	s_nop 0
	v_addc_co_u32_e32 v37, vcc, 0, v35, vcc
	v_add_co_u32_e32 v34, vcc, 0x7101000, v34
	v_lshl_add_u64 v[238:239], v[36:37], 0, v[252:253]
	global_load_dwordx4 v[70:73], v[36:37], off offset:3072
	global_load_dwordx4 v[240:243], v[238:239], off offset:3072
	s_nop 0
	v_addc_co_u32_e32 v35, vcc, 0, v35, vcc
	v_lshl_add_u64 v[238:239], v[34:35], 0, v[252:253]
	global_load_dwordx4 v[78:81], v[34:35], off
	global_load_dwordx4 v[240:243], v[238:239], off
	v_lshl_add_u64 v[238:239], v[34:35], 0, v[252:253]
	global_load_dwordx4 v[74:77], v[34:35], off offset:1024
	global_load_dwordx4 v[240:243], v[238:239], off offset:1024
	v_lshl_add_u64 v[34:35], s[28:29], 0, v[0:1]
	v_add_co_u32_e32 v36, vcc, s4, v34
	s_mov_b32 s4, 0x7101000
	s_nop 0
	v_addc_co_u32_e32 v37, vcc, 0, v35, vcc
	v_add_co_u32_e32 v34, vcc, s4, v34
	v_lshl_add_u64 v[238:239], v[36:37], 0, v[252:253]
	global_load_dwordx4 v[58:61], v[36:37], off offset:3072
	global_load_dwordx4 v[240:243], v[238:239], off offset:3072
	s_nop 0
	v_addc_co_u32_e32 v35, vcc, 0, v35, vcc
	v_lshl_add_u64 v[238:239], v[34:35], 0, v[252:253]
	global_load_dwordx4 v[66:69], v[34:35], off
	global_load_dwordx4 v[240:243], v[238:239], off
	v_lshl_add_u64 v[238:239], v[34:35], 0, v[252:253]
	global_load_dwordx4 v[62:65], v[34:35], off offset:1024
	global_load_dwordx4 v[240:243], v[238:239], off offset:1024
	s_add_i32 s42, s24, 2
	v_mad_i64_i32 v[34:35], s[4:5], s42, v245, v[82:83]
	v_lshl_add_u64 v[238:239], v[34:35], 0, v[252:253]
	global_load_dwordx4 v[38:41], v[34:35], off offset:3072
	global_load_dwordx4 v[240:243], v[238:239], off offset:3072
	v_add_co_u32_e32 v34, vcc, s45, v34
	s_add_i32 s36, s24, 3
	s_nop 0
	v_addc_co_u32_e32 v35, vcc, 0, v35, vcc
	v_lshl_add_u64 v[238:239], v[34:35], 0, v[252:253]
	global_load_dwordx4 v[54:57], v[34:35], off
	global_load_dwordx4 v[240:243], v[238:239], off
	v_lshl_add_u64 v[238:239], v[34:35], 0, v[252:253]
	global_load_dwordx4 v[50:53], v[34:35], off offset:1024
	global_load_dwordx4 v[240:243], v[238:239], off offset:1024
	v_mad_i64_i32 v[42:43], s[4:5], s36, v245, v[82:83]
	v_lshl_add_u64 v[238:239], v[42:43], 0, v[252:253]
	global_load_dwordx4 v[34:37], v[42:43], off offset:3072
	global_load_dwordx4 v[240:243], v[238:239], off offset:3072
	v_add_co_u32_e32 v42, vcc, s45, v42
	s_ashr_i32 s43, s42, 31
	s_nop 0
	v_addc_co_u32_e32 v43, vcc, 0, v43, vcc
	v_lshl_add_u64 v[238:239], v[42:43], 0, v[252:253]
	global_load_dwordx4 v[46:49], v[42:43], off
	global_load_dwordx4 v[240:243], v[238:239], off
	s_nop 0
	v_lshl_add_u64 v[238:239], v[42:43], 0, v[252:253]
	global_load_dwordx4 v[42:45], v[42:43], off offset:1024
	global_load_dwordx4 v[240:243], v[238:239], off offset:1024
	s_lshl_b64 s[4:5], s[42:43], 11
	s_ashr_i32 s37, s36, 31
	s_add_i32 s24, s24, 4
	s_waitcnt vmcnt(23)
	v_lshlrev_b32_e32 v104, 16, v73
	v_and_b32_e32 v105, 0xffff0000, v73
	s_waitcnt vmcnt(21)
	v_lshlrev_b32_e32 v102, 16, v81
	v_and_b32_e32 v103, 0xffff0000, v81
	s_waitcnt vmcnt(19)
	v_lshlrev_b32_e32 v110, 16, v77
	v_and_b32_e32 v111, 0xffff0000, v77
	v_pk_mul_f32 v[102:103], v[102:103], v[110:111]
	v_pk_mul_f32 v[110:111], v[12:13], v[96:97]
	v_and_b32_e32 v73, 0xffff0000, v80
	v_pk_fma_f32 v[100:101], v[4:5], v[100:101], v[110:111]
	v_lshlrev_b32_e32 v110, 16, v72
	v_and_b32_e32 v111, 0xffff0000, v72
	v_lshlrev_b32_e32 v72, 16, v80
	v_lshlrev_b32_e32 v80, 16, v76
	v_and_b32_e32 v81, 0xffff0000, v76
	v_pk_mul_f32 v[76:77], v[10:11], v[92:93]
	v_pk_mul_f32 v[72:73], v[72:73], v[80:81]
	v_pk_fma_f32 v[76:77], v[2:3], v[98:99], v[76:77]
	v_lshlrev_b32_e32 v114, 16, v75
	v_pk_fma_f32 v[76:77], v[22:23], v[72:73], v[76:77]
	v_and_b32_e32 v115, 0xffff0000, v75
	v_pk_mul_f32 v[80:81], v[76:77], v[110:111]
	v_lshlrev_b32_e32 v76, 16, v79
	v_and_b32_e32 v77, 0xffff0000, v79
	v_pk_mul_f32 v[76:77], v[76:77], v[114:115]
	v_pk_mul_f32 v[114:115], v[16:17], v[90:91]
	v_lshlrev_b32_e32 v98, 16, v71
	v_pk_fma_f32 v[94:95], v[8:9], v[94:95], v[114:115] op_sel:[0,1,0] op_sel_hi:[1,0,1]
	v_and_b32_e32 v99, 0xffff0000, v71
	v_pk_fma_f32 v[94:95], v[20:21], v[76:77], v[94:95]
	v_and_b32_e32 v71, 0xffff0000, v78
	v_pk_mul_f32 v[94:95], v[94:95], v[98:99]
	v_lshlrev_b32_e32 v98, 16, v70
	v_and_b32_e32 v99, 0xffff0000, v70
	v_lshlrev_b32_e32 v70, 16, v78
	v_lshlrev_b32_e32 v78, 16, v74
	v_and_b32_e32 v79, 0xffff0000, v74
	v_pk_mul_f32 v[74:75], v[14:15], v[88:89]
	v_pk_mul_f32 v[70:71], v[70:71], v[78:79]
	v_pk_fma_f32 v[74:75], v[6:7], v[86:87], v[74:75] op_sel:[0,1,0] op_sel_hi:[1,0,1]
	s_waitcnt vmcnt(13)
	v_lshlrev_b32_e32 v118, 16, v65
	v_pk_fma_f32 v[74:75], v[18:19], v[70:71], v[74:75]
	v_and_b32_e32 v119, 0xffff0000, v65
	v_pk_mul_f32 v[78:79], v[74:75], v[98:99]
	v_lshlrev_b32_e32 v74, 16, v69
	v_and_b32_e32 v75, 0xffff0000, v69
	v_pk_mul_f32 v[74:75], v[74:75], v[118:119]
	v_pk_mul_f32 v[118:119], v[12:13], v[102:103]
	v_lshlrev_b32_e32 v86, 16, v61
	v_and_b32_e32 v87, 0xffff0000, v61
	v_pk_fma_f32 v[96:97], v[4:5], v[96:97], v[118:119]
	v_lshlrev_b32_e32 v118, 16, v60
	v_and_b32_e32 v119, 0xffff0000, v60
	v_lshlrev_b32_e32 v60, 16, v68
	v_and_b32_e32 v61, 0xffff0000, v68
	v_lshlrev_b32_e32 v68, 16, v64
	v_and_b32_e32 v69, 0xffff0000, v64
	v_pk_mul_f32 v[64:65], v[10:11], v[72:73]
	v_pk_mul_f32 v[60:61], v[60:61], v[68:69]
	v_pk_fma_f32 v[64:65], v[2:3], v[92:93], v[64:65]
	v_lshlrev_b32_e32 v120, 16, v63
	v_pk_fma_f32 v[64:65], v[22:23], v[60:61], v[64:65]
	v_and_b32_e32 v121, 0xffff0000, v63
	v_pk_mul_f32 v[68:69], v[64:65], v[118:119]
	v_lshlrev_b32_e32 v64, 16, v67
	v_and_b32_e32 v65, 0xffff0000, v67
	v_pk_mul_f32 v[64:65], v[64:65], v[120:121]
	v_pk_mul_f32 v[120:121], v[16:17], v[76:77]
	v_lshlrev_b32_e32 v118, 16, v59
	v_and_b32_e32 v119, 0xffff0000, v59
	v_pk_fma_f32 v[90:91], v[8:9], v[90:91], v[120:121]
	v_lshlrev_b32_e32 v120, 16, v58
	v_and_b32_e32 v121, 0xffff0000, v58
	v_lshlrev_b32_e32 v58, 16, v66
	v_and_b32_e32 v59, 0xffff0000, v66
	v_lshlrev_b32_e32 v66, 16, v62
	v_and_b32_e32 v67, 0xffff0000, v62
	v_pk_mul_f32 v[62:63], v[14:15], v[70:71]
	v_pk_mul_f32 v[58:59], v[58:59], v[66:67]
	v_pk_fma_f32 v[62:63], v[6:7], v[88:89], v[62:63]
	v_pk_fma_f32 v[90:91], v[20:21], v[64:65], v[90:91]
	v_pk_fma_f32 v[62:63], v[18:19], v[58:59], v[62:63]
	v_pk_mul_f32 v[116:117], v[78:79], v[78:79]
	v_pk_mul_f32 v[62:63], v[62:63], v[120:121]
	v_pk_mul_f32 v[90:91], v[90:91], v[118:119]
	v_pk_mul_f32 v[66:67], v[62:63], v[62:63]
	v_pk_mul_f32 v[114:115], v[94:95], v[94:95]
	v_pk_mul_f32 v[118:119], v[90:91], v[90:91]
	v_mov_b32_e32 v88, v66
	v_mov_b32_e32 v89, v116
	v_mov_b32_e32 v116, v67
	v_pk_add_f32 v[66:67], v[88:89], v[116:117]
	v_mov_b32_e32 v88, v118
	v_mov_b32_e32 v89, v114
	v_pk_fma_f32 v[100:101], v[24:25], v[102:103], v[100:101]
	v_pk_mul_f32 v[110:111], v[80:81], v[80:81]
	v_pk_fma_f32 v[96:97], v[24:25], v[74:75], v[96:97]
	v_pk_mul_f32 v[92:93], v[68:69], v[68:69]
	v_pk_add_f32 v[66:67], v[88:89], v[66:67]
	v_mov_b32_e32 v114, v119
	v_pk_mul_f32 v[100:101], v[100:101], v[104:105]
	v_pk_mul_f32 v[86:87], v[96:97], v[86:87]
	v_pk_add_f32 v[66:67], v[114:115], v[66:67]
	v_mov_b32_e32 v88, v92
	v_mov_b32_e32 v89, v110
	v_pk_mul_f32 v[104:105], v[100:101], v[100:101]
	v_pk_mul_f32 v[96:97], v[86:87], v[86:87]
	v_pk_add_f32 v[66:67], v[88:89], v[66:67]
	v_mov_b32_e32 v110, v93
	v_pk_add_f32 v[66:67], v[110:111], v[66:67]
	v_mov_b32_e32 v88, v96
	v_mov_b32_e32 v89, v104
	v_pk_add_f32 v[66:67], v[88:89], v[66:67]
	v_mov_b32_e32 v104, v97
	v_pk_add_f32 v[66:67], v[104:105], v[66:67]
	ds_bpermute_b32 v89, v106, v67
	ds_bpermute_b32 v88, v106, v66
	v_mov_b64_e32 v[104:105], s[44:45]
	v_lshl_add_u64 v[98:99], s[30:31], 0, v[0:1]
	s_waitcnt lgkmcnt(0)
	v_pk_add_f32 v[66:67], v[66:67], v[88:89]
	ds_bpermute_b32 v89, v107, v67
	ds_bpermute_b32 v88, v107, v66
	s_waitcnt lgkmcnt(0)
	v_pk_add_f32 v[66:67], v[66:67], v[88:89]
	ds_bpermute_b32 v89, v108, v67
	ds_bpermute_b32 v88, v108, v66
	s_waitcnt lgkmcnt(0)
	v_pk_add_f32 v[66:67], v[66:67], v[88:89]
	s_nop 0
	v_pk_fma_f32 v[66:67], v[66:67], s[46:47], v[104:105] op_sel_hi:[1,0,0]
	s_nop 0
	v_mul_f32_e32 v88, 0x4b800000, v67
	v_cmp_gt_f32_e64 s[40:41], s10, v67
	v_cmp_gt_f32_e32 vcc, s10, v66
	s_nop 0
	v_cndmask_b32_e64 v67, v67, v88, s[40:41]
	v_rsq_f32_e32 v67, v67
	s_nop 0
	v_mul_f32_e32 v88, 0x45800000, v67
	v_cndmask_b32_e64 v88, v67, v88, s[40:41]
	v_mul_f32_e32 v67, 0x4b800000, v66
	v_cndmask_b32_e32 v66, v66, v67, vcc
	v_rsq_f32_e32 v66, v66
	v_pk_mul_f32 v[78:79], v[78:79], v[88:89] op_sel_hi:[1,0]
	v_pk_mul_f32 v[92:93], v[94:95], v[88:89] op_sel_hi:[1,0]
	v_pk_mul_f32 v[80:81], v[80:81], v[88:89] op_sel_hi:[1,0]
	v_pk_mul_f32 v[88:89], v[100:101], v[88:89] op_sel_hi:[1,0]
	v_pk_mul_f32 v[78:79], v[30:31], v[78:79]
	v_pk_mul_f32 v[92:93], v[32:33], v[92:93]
	v_pk_mul_f32 v[80:81], v[26:27], v[80:81]
	v_pk_mul_f32 v[88:89], v[28:29], v[88:89]
	v_cvt_pk_bf16_f32 v78, v78, v79
	v_cvt_pk_bf16_f32 v79, v92, v93
	v_cvt_pk_bf16_f32 v80, v80, v81
	v_cvt_pk_bf16_f32 v81, v88, v89
	v_mul_f32_e32 v67, 0x45800000, v66
	global_store_dwordx4 v[98:99], v[78:81], off
	s_nop 1
	v_cndmask_b32_e32 v78, v66, v67, vcc
	v_pk_mul_f32 v[62:63], v[62:63], v[78:79] op_sel_hi:[1,0]
	s_nop 0
	v_pk_mul_f32 v[62:63], v[30:31], v[62:63]
	s_nop 0
	v_cvt_pk_bf16_f32 v66, v62, v63
	v_pk_mul_f32 v[62:63], v[90:91], v[78:79] op_sel_hi:[1,0]
	s_nop 0
	v_pk_mul_f32 v[62:63], v[32:33], v[62:63]
	s_nop 0
	v_cvt_pk_bf16_f32 v67, v62, v63
	v_pk_mul_f32 v[62:63], v[68:69], v[78:79] op_sel_hi:[1,0]
	s_nop 0
	v_pk_mul_f32 v[62:63], v[26:27], v[62:63]
	s_nop 0
	v_cvt_pk_bf16_f32 v68, v62, v63
	v_pk_mul_f32 v[62:63], v[86:87], v[78:79] op_sel_hi:[1,0]
	s_nop 0
	v_pk_mul_f32 v[62:63], v[28:29], v[62:63]
	s_nop 0
	v_cvt_pk_bf16_f32 v69, v62, v63
	v_lshl_add_u64 v[62:63], s[26:27], 0, v[0:1]
	global_store_dwordx4 v[62:63], v[66:69], off
	s_waitcnt vmcnt(11)
	v_and_b32_e32 v62, 0xffff0000, v54
	v_lshlrev_b32_e32 v63, 16, v54
	s_waitcnt vmcnt(9)
	v_and_b32_e32 v66, 0xffff0000, v50
	v_lshlrev_b32_e32 v67, 16, v50
	v_and_b32_e32 v54, 0xffff0000, v55
	v_lshlrev_b32_e32 v55, 16, v55
	v_and_b32_e32 v50, 0xffff0000, v51
	v_lshlrev_b32_e32 v51, 16, v51
	v_pk_mul_f32 v[94:95], v[54:55], v[50:51]
	v_lshlrev_b32_e32 v50, 16, v56
	v_and_b32_e32 v51, 0xffff0000, v56
	v_lshlrev_b32_e32 v54, 16, v52
	v_and_b32_e32 v55, 0xffff0000, v52
	v_pk_mul_f32 v[98:99], v[50:51], v[54:55]
	v_lshlrev_b32_e32 v50, 16, v57
	v_and_b32_e32 v51, 0xffff0000, v57
	v_lshlrev_b32_e32 v52, 16, v53
	v_and_b32_e32 v53, 0xffff0000, v53
	v_pk_mul_f32 v[86:87], v[62:63], v[66:67]
	v_pk_mul_f32 v[100:101], v[50:51], v[52:53]
	v_lshlrev_b32_e32 v50, 16, v41
	v_and_b32_e32 v51, 0xffff0000, v41
	v_lshlrev_b32_e32 v54, 16, v40
	v_and_b32_e32 v55, 0xffff0000, v40
	v_pk_mul_f32 v[40:41], v[10:11], v[60:61]
	v_lshlrev_b32_e32 v56, 16, v39
	v_and_b32_e32 v57, 0xffff0000, v39
	v_lshlrev_b32_e32 v66, 16, v38
	v_and_b32_e32 v67, 0xffff0000, v38
	v_pk_mul_f32 v[38:39], v[14:15], v[58:59]
	v_pk_fma_f32 v[40:41], v[2:3], v[72:73], v[40:41]
	v_pk_fma_f32 v[38:39], v[6:7], v[70:71], v[38:39]
	s_waitcnt vmcnt(5)
	v_lshlrev_b32_e32 v70, 16, v46
	v_and_b32_e32 v71, 0xffff0000, v46
	s_waitcnt vmcnt(3)
	v_lshlrev_b32_e32 v72, 16, v42
	v_and_b32_e32 v73, 0xffff0000, v42
	v_lshlrev_b32_e32 v46, 16, v47
	v_and_b32_e32 v47, 0xffff0000, v47
	v_lshlrev_b32_e32 v42, 16, v43
	v_and_b32_e32 v43, 0xffff0000, v43
	v_pk_mul_f32 v[90:91], v[46:47], v[42:43]
	v_lshlrev_b32_e32 v42, 16, v48
	v_and_b32_e32 v43, 0xffff0000, v48
	v_lshlrev_b32_e32 v46, 16, v44
	v_and_b32_e32 v47, 0xffff0000, v44
	v_pk_mul_f32 v[92:93], v[42:43], v[46:47]
	v_lshlrev_b32_e32 v42, 16, v49
	v_and_b32_e32 v43, 0xffff0000, v49
	v_lshlrev_b32_e32 v44, 16, v45
	v_and_b32_e32 v45, 0xffff0000, v45
	v_pk_mul_f32 v[96:97], v[42:43], v[44:45]
	v_lshlrev_b32_e32 v42, 16, v37
	v_and_b32_e32 v43, 0xffff0000, v37
	v_lshlrev_b32_e32 v46, 16, v36
	v_and_b32_e32 v47, 0xffff0000, v36
	v_pk_mul_f32 v[36:37], v[10:11], v[98:99]
	v_pk_mul_f32 v[62:63], v[16:17], v[64:65]
	v_pk_fma_f32 v[36:37], v[2:3], v[60:61], v[36:37]
	v_pk_mul_f32 v[60:61], v[16:17], v[94:95] op_sel:[0,1] op_sel_hi:[1,0]
	v_lshlrev_b32_e32 v48, 16, v35
	v_and_b32_e32 v49, 0xffff0000, v35
	v_pk_fma_f32 v[60:61], v[8:9], v[64:65], v[60:61]
	v_lshlrev_b32_e32 v64, 16, v34
	v_and_b32_e32 v65, 0xffff0000, v34
	v_pk_mul_f32 v[34:35], v[14:15], v[86:87] op_sel:[0,1] op_sel_hi:[1,0]
	v_pk_mul_f32 v[88:89], v[70:71], v[72:73]
	v_pk_fma_f32 v[34:35], v[6:7], v[58:59], v[34:35]
	v_pk_fma_f32 v[62:63], v[8:9], v[76:77], v[62:63]
	v_pk_fma_f32 v[38:39], v[18:19], v[86:87], v[38:39] op_sel:[0,1,0] op_sel_hi:[1,0,1]
	v_pk_fma_f32 v[34:35], v[18:19], v[88:89], v[34:35]
	v_pk_fma_f32 v[62:63], v[20:21], v[94:95], v[62:63] op_sel:[0,1,0] op_sel_hi:[1,0,1]
	v_pk_mul_f32 v[38:39], v[38:39], v[66:67]
	v_pk_fma_f32 v[60:61], v[20:21], v[90:91], v[60:61]
	v_pk_mul_f32 v[58:59], v[34:35], v[64:65]
	v_pk_mul_f32 v[56:57], v[62:63], v[56:57]
	v_pk_mul_f32 v[66:67], v[38:39], v[38:39]
	v_pk_mul_f32 v[48:49], v[60:61], v[48:49]
	v_pk_mul_f32 v[34:35], v[58:59], v[58:59]
	v_pk_mul_f32 v[52:53], v[12:13], v[74:75]
	v_pk_fma_f32 v[40:41], v[22:23], v[98:99], v[40:41]
	v_pk_mul_f32 v[62:63], v[56:57], v[56:57]
	v_pk_mul_f32 v[44:45], v[12:13], v[100:101]
	v_pk_fma_f32 v[36:37], v[22:23], v[92:93], v[36:37]
	v_pk_mul_f32 v[60:61], v[48:49], v[48:49]
	v_mov_b32_e32 v64, v34
	v_mov_b32_e32 v65, v66
	v_mov_b32_e32 v66, v35
	v_pk_fma_f32 v[52:53], v[4:5], v[102:103], v[52:53]
	v_pk_mul_f32 v[40:41], v[40:41], v[54:55]
	v_pk_fma_f32 v[44:45], v[4:5], v[74:75], v[44:45]
	v_pk_mul_f32 v[46:47], v[36:37], v[46:47]
	v_pk_add_f32 v[34:35], v[64:65], v[66:67]
	v_mov_b32_e32 v64, v60
	v_mov_b32_e32 v65, v62
	v_pk_fma_f32 v[52:53], v[24:25], v[100:101], v[52:53]
	v_pk_mul_f32 v[54:55], v[40:41], v[40:41]
	v_pk_fma_f32 v[44:45], v[24:25], v[96:97], v[44:45]
	v_pk_mul_f32 v[36:37], v[46:47], v[46:47]
	v_pk_add_f32 v[34:35], v[64:65], v[34:35]
	v_mov_b32_e32 v62, v61
	v_pk_mul_f32 v[50:51], v[52:53], v[50:51]
	v_pk_mul_f32 v[42:43], v[44:45], v[42:43]
	v_pk_add_f32 v[34:35], v[62:63], v[34:35]
	v_mov_b32_e32 v60, v36
	v_mov_b32_e32 v61, v54
	v_pk_mul_f32 v[52:53], v[50:51], v[50:51]
	v_pk_mul_f32 v[44:45], v[42:43], v[42:43]
	v_pk_add_f32 v[34:35], v[60:61], v[34:35]
	v_mov_b32_e32 v54, v37
	v_pk_add_f32 v[34:35], v[54:55], v[34:35]
	v_mov_b32_e32 v36, v44
	v_mov_b32_e32 v37, v52
	v_pk_add_f32 v[34:35], v[36:37], v[34:35]
	v_mov_b32_e32 v52, v45
	v_pk_add_f32 v[34:35], v[52:53], v[34:35]
	ds_bpermute_b32 v37, v106, v35
	ds_bpermute_b32 v36, v106, v34
	v_lshl_add_u64 v[68:69], v[84:85], 0, s[4:5]
	s_lshl_b64 s[4:5], s[36:37], 11
	s_add_u32 s26, s26, 0x2000
	s_addc_u32 s27, s27, 0
	s_waitcnt lgkmcnt(0)
	v_pk_add_f32 v[34:35], v[34:35], v[36:37]
	ds_bpermute_b32 v37, v107, v35
	ds_bpermute_b32 v36, v107, v34
	s_add_u32 s28, s28, 0x6000
	s_addc_u32 s29, s29, 0
	s_add_u32 s30, s30, 0x2000
	s_addc_u32 s31, s31, 0
	s_waitcnt lgkmcnt(0)
	v_pk_add_f32 v[34:35], v[34:35], v[36:37]
	ds_bpermute_b32 v37, v108, v35
	ds_bpermute_b32 v36, v108, v34
	s_add_u32 s34, s34, 0x6000
	s_addc_u32 s35, s35, 0
	s_cmp_ge_i32 s24, s39
	s_waitcnt lgkmcnt(0)
	v_pk_add_f32 v[34:35], v[34:35], v[36:37]
	s_nop 0
	v_pk_fma_f32 v[44:45], v[34:35], s[46:47], v[104:105] op_sel_hi:[1,0,0]
	s_nop 0
	v_mul_f32_e32 v34, 0x4b800000, v45
	v_cmp_gt_f32_e64 s[40:41], s10, v45
	v_cmp_gt_f32_e32 vcc, s10, v44
	s_nop 0
	v_cndmask_b32_e64 v34, v45, v34, s[40:41]
	v_rsq_f32_e32 v34, v34
	s_nop 0
	v_mul_f32_e32 v35, 0x45800000, v34
	v_cndmask_b32_e64 v52, v34, v35, s[40:41]
	v_pk_mul_f32 v[34:35], v[38:39], v[52:53] op_sel_hi:[1,0]
	v_pk_mul_f32 v[36:37], v[56:57], v[52:53] op_sel_hi:[1,0]
	v_pk_mul_f32 v[34:35], v[30:31], v[34:35]
	v_pk_mul_f32 v[36:37], v[32:33], v[36:37]
	v_cvt_pk_bf16_f32 v34, v34, v35
	v_cvt_pk_bf16_f32 v35, v36, v37
	v_pk_mul_f32 v[36:37], v[40:41], v[52:53] op_sel_hi:[1,0]
	v_pk_mul_f32 v[38:39], v[50:51], v[52:53] op_sel_hi:[1,0]
	v_pk_mul_f32 v[36:37], v[26:27], v[36:37]
	v_pk_mul_f32 v[38:39], v[28:29], v[38:39]
	v_cvt_pk_bf16_f32 v36, v36, v37
	v_cvt_pk_bf16_f32 v37, v38, v39
	global_store_dwordx4 v[68:69], v[34:37], off offset:1024
	s_nop 1
	v_mul_f32_e32 v34, 0x4b800000, v44
	v_cndmask_b32_e32 v34, v44, v34, vcc
	v_rsq_f32_e32 v34, v34
	s_nop 0
	v_mul_f32_e32 v35, 0x45800000, v34
	v_cndmask_b32_e32 v38, v34, v35, vcc
	v_pk_mul_f32 v[34:35], v[58:59], v[38:39] op_sel_hi:[1,0]
	v_pk_mul_f32 v[36:37], v[48:49], v[38:39] op_sel_hi:[1,0]
	v_pk_mul_f32 v[34:35], v[30:31], v[34:35]
	v_pk_mul_f32 v[36:37], v[32:33], v[36:37]
	v_cvt_pk_bf16_f32 v34, v34, v35
	v_cvt_pk_bf16_f32 v35, v36, v37
	v_pk_mul_f32 v[36:37], v[46:47], v[38:39] op_sel_hi:[1,0]
	v_pk_mul_f32 v[38:39], v[42:43], v[38:39] op_sel_hi:[1,0]
	v_pk_mul_f32 v[36:37], v[26:27], v[36:37]
	v_pk_mul_f32 v[38:39], v[28:29], v[38:39]
	v_cvt_pk_bf16_f32 v36, v36, v37
	v_cvt_pk_bf16_f32 v37, v38, v39
	v_lshl_add_u64 v[38:39], v[84:85], 0, s[4:5]
	global_store_dwordx4 v[38:39], v[34:37], off offset:1024
	s_cbranch_scc0 .LBB0_113
